# v23 + nt on the attention-unit output stores (MIX/DT, read once by mixpost)
# speedup vs baseline: 1.0087x; 1.0019x over previous
; template <int OFF = 0, class V> __device__ __forceinline__ void st_wt16(void* p, V v) { static_assert(sizeof(V) == 16, ""); asm volatile("global_store_dwordx4 %0, %1, off offset:%2 sc1\n\ts_nop 1" :: "v"(p), "v"(v), "i"(OFF)); }
; #define ALAS __attribute__((address_space(3)))
; __device__ __forceinline__ int crow(int r, int hi) { return (r & 3) + 8 * (r >> 2) + 4 * hi; }
; __device__ __forceinline__ unsigned cvtpk(float lo, float hi) { unsigned r; asm volatile("v_cvt_pk_bf16_f32 %0, %1, %2" : "=v"(r) : "v"(lo), "v"(hi)); return r; }
; template <int LD, class FillFn> ...
;     ...
;   if (hi == 0) li_l[r32] = l_reg; asm volatile("s_waitcnt lgkmcnt(0)" ::: "memory");
;   float rli[16];
; #pragma unroll
;   for (int r = 0; r < 16; ++r) rli[r] = __builtin_amdgcn_rcpf(li_l[crow(r, hi)]);
;   { lptr stg = lds + OFF_STG + wid * 4096; const int psh = (mode == MODE_D) ? 10 : 12;
;     bf16* Ob = (bf16*)Op + ((unsigned)(wid * QBLK) << psh);
; #pragma unroll
;     for (int p = 0; p < 2; ++p) {
; #pragma unroll
;       for (int r = 0; r < 16; ++r) { const unsigned w = cvtpk(o[2 * p][r] * rli[r], o[2 * p + 1][r] * rli[r]); ALAS unsigned short* sp = (ALAS unsigned short*)(stg + crow(r, hi) * 128 + r32 * 2);
;         sp[0] = (unsigned short)w; sp[32] = (unsigned short)(w >> 16); }
;       asm volatile("s_waitcnt lgkmcnt(0)" ::: "memory");
; #pragma unroll
;       for (int i = 0; i < 4; ++i) { const int row = i * 8 + (lane >> 3), ch = lane & 7; const u32x4 v = *(const ALAS u32x4*)(stg + row * 128 + ch * 16);
;         st_wt16(Ob + (((unsigned)row << psh) + p * 64 + ch * 8), v); }
;       asm volatile("s_waitcnt lgkmcnt(0)" ::: "memory"); } }
.LBB0_332:
	s_or_b64 exec, exec, s[2:3]
	s_waitcnt lgkmcnt(0)
	v_add_u32_e32 v72, s31, v224
	ds_read_b128 v[64:67], v72
	ds_read_b128 v[68:71], v72 offset:32
	s_lshl_b32 s1, s41, 12
	s_add_i32 s1, s1, 0
	s_add_i32 s1, s1, 0x12800
	s_waitcnt lgkmcnt(1)
	v_rcp_f32_e32 v73, v64
	v_rcp_f32_e32 v74, v65
	v_rcp_f32_e32 v75, v66
	v_rcp_f32_e32 v76, v67
	s_waitcnt lgkmcnt(0)
	v_rcp_f32_e32 v77, v68
	ds_read_b128 v[64:67], v72 offset:64
	v_rcp_f32_e32 v78, v69
	v_rcp_f32_e32 v79, v70
	v_rcp_f32_e32 v80, v71
	ds_read_b128 v[68:71], v72 offset:96
	v_lshlrev_b32_e32 v72, 9, v222
	v_lshlrev_b32_e32 v81, 1, v221
	v_mul_f32_e32 v32, v32, v73
	v_add3_u32 v72, s1, v72, v81
	v_mul_f32_e32 v48, v48, v73
	v_cvt_pk_bf16_f32 v32, v48, v32
	ds_write_b16 v72, v32
	ds_write_b16_d16_hi v72, v32 offset:64
	v_mul_f32_e32 v32, v49, v74
	v_mul_f32_e32 v33, v33, v74
	v_cvt_pk_bf16_f32 v32, v32, v33
	ds_write_b16 v72, v32 offset:128
	ds_write_b16_d16_hi v72, v32 offset:192
	v_mul_f32_e32 v32, v50, v75
	v_mul_f32_e32 v33, v34, v75
	v_cvt_pk_bf16_f32 v32, v32, v33
	ds_write_b16 v72, v32 offset:256
	ds_write_b16_d16_hi v72, v32 offset:320
	v_mul_f32_e32 v32, v51, v76
	v_mul_f32_e32 v33, v35, v76
	v_cvt_pk_bf16_f32 v32, v32, v33
	ds_write_b16 v72, v32 offset:384
	ds_write_b16_d16_hi v72, v32 offset:448
	v_mul_f32_e32 v32, v52, v77
	v_mul_f32_e32 v33, v36, v77
	v_cvt_pk_bf16_f32 v32, v32, v33
	ds_write_b16 v72, v32 offset:1024
	ds_write_b16_d16_hi v72, v32 offset:1088
	v_mul_f32_e32 v32, v53, v78
	v_mul_f32_e32 v33, v37, v78
	v_cvt_pk_bf16_f32 v32, v32, v33
	s_waitcnt lgkmcnt(11)
	v_rcp_f32_e32 v64, v64
	ds_write_b16 v72, v32 offset:1152
	ds_write_b16_d16_hi v72, v32 offset:1216
	v_mul_f32_e32 v32, v54, v79
	v_mul_f32_e32 v33, v38, v79
	v_cvt_pk_bf16_f32 v32, v32, v33
	v_rcp_f32_e32 v65, v65
	ds_write_b16 v72, v32 offset:1280
	ds_write_b16_d16_hi v72, v32 offset:1344
	v_mul_f32_e32 v32, v55, v80
	v_mul_f32_e32 v33, v39, v80
	v_cvt_pk_bf16_f32 v32, v32, v33
	v_rcp_f32_e32 v66, v66
	ds_write_b16 v72, v32 offset:1408
	ds_write_b16_d16_hi v72, v32 offset:1472
	v_mul_f32_e32 v32, v56, v64
	v_mul_f32_e32 v33, v40, v64
	v_cvt_pk_bf16_f32 v32, v32, v33
	v_rcp_f32_e32 v67, v67
	ds_write_b16 v72, v32 offset:2048
	ds_write_b16_d16_hi v72, v32 offset:2112
	v_mul_f32_e32 v32, v57, v65
	v_mul_f32_e32 v33, v41, v65
	v_cvt_pk_bf16_f32 v32, v32, v33
	s_waitcnt lgkmcnt(14)
	v_rcp_f32_e32 v68, v68
	ds_write_b16 v72, v32 offset:2176
	ds_write_b16_d16_hi v72, v32 offset:2240
	v_mul_f32_e32 v32, v58, v66
	v_mul_f32_e32 v33, v42, v66
	v_cvt_pk_bf16_f32 v32, v32, v33
	v_rcp_f32_e32 v69, v69
	ds_write_b16 v72, v32 offset:2304
	ds_write_b16_d16_hi v72, v32 offset:2368
	v_mul_f32_e32 v32, v59, v67
	v_mul_f32_e32 v33, v43, v67
	v_cvt_pk_bf16_f32 v32, v32, v33
	v_rcp_f32_e32 v70, v70
	ds_write_b16 v72, v32 offset:2432
	ds_write_b16_d16_hi v72, v32 offset:2496
	v_mul_f32_e32 v32, v60, v68
	v_mul_f32_e32 v33, v44, v68
	v_cvt_pk_bf16_f32 v32, v32, v33
	v_rcp_f32_e32 v71, v71
	ds_write_b16 v72, v32 offset:3072
	ds_write_b16_d16_hi v72, v32 offset:3136
	v_mul_f32_e32 v32, v61, v69
	v_mul_f32_e32 v33, v45, v69
	v_cvt_pk_bf16_f32 v32, v32, v33
	s_and_b64 s[2:3], s[24:25], exec
	ds_write_b16 v72, v32 offset:3200
	ds_write_b16_d16_hi v72, v32 offset:3264
	v_mul_f32_e32 v32, v62, v70
	s_cselect_b32 s4, 10, 12
	v_mul_f32_e32 v33, v46, v70
	v_cvt_pk_bf16_f32 v32, v32, v33
	s_lshl_b32 s12, s40, s4
	ds_write_b16 v72, v32 offset:3328
	ds_write_b16_d16_hi v72, v32 offset:3392
	v_mul_f32_e32 v32, v63, v71
	s_lshl_b64 s[2:3], s[12:13], 1
	v_readlane_b32 s8, v255, 14
	v_lshrrev_b32_e32 v81, 3, v200
	v_mul_f32_e32 v33, v47, v71
	v_cvt_pk_bf16_f32 v32, v32, v33
	v_lshlrev_b32_e32 v42, 3, v223
	v_readlane_b32 s9, v255, 15
	s_add_u32 s2, s8, s2
	v_lshl_add_u32 v82, v223, 4, s1
	ds_write_b16 v72, v32 offset:3456
	ds_write_b16_d16_hi v72, v32 offset:3520
	v_lshl_or_b32 v36, v81, s4, v42
	v_or_b32_e32 v38, 8, v81
	s_addc_u32 s3, s9, s3
	v_lshl_add_u32 v83, v81, 7, v82
	s_waitcnt lgkmcnt(0)
	v_lshlrev_b32_e32 v200, 1, v36
	v_lshl_add_u32 v44, v38, 7, v82
	v_lshl_or_b32 v38, v38, s4, v42
	v_or_b32_e32 v40, 16, v81
	ds_read_b128 v[32:35], v83
	v_lshl_add_u64 v[36:37], s[2:3], 0, v[200:201]
	v_lshlrev_b32_e32 v200, 1, v38
	v_lshl_add_u32 v45, v40, 7, v82
	v_lshl_or_b32 v40, v40, s4, v42
	v_or_b32_e32 v43, 24, v81
	s_waitcnt lgkmcnt(0)
; template <int OFF = 0, class V> __device__ __forceinline__ void st_wt16(void* p, V v) { static_assert(sizeof(V) == 16, ""); asm volatile("global_store_dwordx4 %0, %1, off offset:%2 sc1\n\ts_nop 1" :: "v"(p), "v"(v), "i"(OFF)); }
; #define ALAS __attribute__((address_space(3)))
; __device__ __forceinline__ int crow(int r, int hi) { return (r & 3) + 8 * (r >> 2) + 4 * hi; }
; __device__ __forceinline__ unsigned cvtpk(float lo, float hi) { unsigned r; asm volatile("v_cvt_pk_bf16_f32 %0, %1, %2" : "=v"(r) : "v"(lo), "v"(hi)); return r; }
; template <int LD, class FillFn> ...
;     ...
;     for (int p = 0; p < 2; ++p) {
; #pragma unroll
;       for (int r = 0; r < 16; ++r) { const unsigned w = cvtpk(o[2 * p][r] * rli[r], o[2 * p + 1][r] * rli[r]); ALAS unsigned short* sp = (ALAS unsigned short*)(stg + crow(r, hi) * 128 + r32 * 2);
;         sp[0] = (unsigned short)w; sp[32] = (unsigned short)(w >> 16); }
;       asm volatile("s_waitcnt lgkmcnt(0)" ::: "memory");
; #pragma unroll
;       for (int i = 0; i < 4; ++i) { const int row = i * 8 + (lane >> 3), ch = lane & 7; const u32x4 v = *(const ALAS u32x4*)(stg + row * 128 + ch * 16);
;         st_wt16(Ob + (((unsigned)row << psh) + p * 64 + ch * 8), v); }
;       asm volatile("s_waitcnt lgkmcnt(0)" ::: "memory"); } }
	global_store_dwordx4 v[36:37], v[32:35], off offset:0 sc1 nt
	s_nop 1
	ds_read_b128 v[32:35], v44
	v_lshl_add_u64 v[38:39], s[2:3], 0, v[200:201]
	v_lshlrev_b32_e32 v200, 1, v40
	v_lshl_or_b32 v42, v43, s4, v42
	s_waitcnt lgkmcnt(0)
	global_store_dwordx4 v[38:39], v[32:35], off offset:0 sc1 nt
	s_nop 1
	ds_read_b128 v[32:35], v45
	v_lshl_add_u64 v[40:41], s[2:3], 0, v[200:201]
	v_lshl_add_u32 v46, v43, 7, v82
	v_lshlrev_b32_e32 v200, 1, v42
	v_mul_f32_e32 v0, v0, v73
	s_waitcnt lgkmcnt(0)
	global_store_dwordx4 v[40:41], v[32:35], off offset:0 sc1 nt
	s_nop 1
	ds_read_b128 v[32:35], v46
	v_lshl_add_u64 v[42:43], s[2:3], 0, v[200:201]
	s_waitcnt lgkmcnt(0)
	global_store_dwordx4 v[42:43], v[32:35], off offset:0 sc1 nt
	s_nop 1
	s_waitcnt lgkmcnt(0)
	v_mul_f32_e32 v16, v16, v73
	v_cvt_pk_bf16_f32 v0, v16, v0
	ds_write_b16 v72, v0
	ds_write_b16_d16_hi v72, v0 offset:64
	v_mul_f32_e32 v0, v17, v74
	v_mul_f32_e32 v1, v1, v74
	v_cvt_pk_bf16_f32 v0, v0, v1
	ds_write_b16 v72, v0 offset:128
	ds_write_b16_d16_hi v72, v0 offset:192
	v_mul_f32_e32 v0, v18, v75
	v_mul_f32_e32 v1, v2, v75
	v_cvt_pk_bf16_f32 v0, v0, v1
	ds_write_b16 v72, v0 offset:256
	ds_write_b16_d16_hi v72, v0 offset:320
	v_mul_f32_e32 v0, v19, v76
	v_mul_f32_e32 v1, v3, v76
	v_cvt_pk_bf16_f32 v0, v0, v1
	ds_write_b16 v72, v0 offset:384
	ds_write_b16_d16_hi v72, v0 offset:448
	v_mul_f32_e32 v0, v20, v77
	v_mul_f32_e32 v1, v4, v77
	v_cvt_pk_bf16_f32 v0, v0, v1
	ds_write_b16 v72, v0 offset:1024
	ds_write_b16_d16_hi v72, v0 offset:1088
	v_mul_f32_e32 v0, v21, v78
	v_mul_f32_e32 v1, v5, v78
	v_cvt_pk_bf16_f32 v0, v0, v1
	ds_write_b16 v72, v0 offset:1152
	ds_write_b16_d16_hi v72, v0 offset:1216
	v_mul_f32_e32 v0, v22, v79
	v_mul_f32_e32 v1, v6, v79
	v_cvt_pk_bf16_f32 v0, v0, v1
	ds_write_b16 v72, v0 offset:1280
	ds_write_b16_d16_hi v72, v0 offset:1344
	v_mul_f32_e32 v0, v23, v80
	v_mul_f32_e32 v1, v7, v80
	v_cvt_pk_bf16_f32 v0, v0, v1
	ds_write_b16 v72, v0 offset:1408
	ds_write_b16_d16_hi v72, v0 offset:1472
	v_mul_f32_e32 v0, v24, v64
	v_mul_f32_e32 v1, v8, v64
	v_cvt_pk_bf16_f32 v0, v0, v1
	ds_write_b16 v72, v0 offset:2048
	ds_write_b16_d16_hi v72, v0 offset:2112
	v_mul_f32_e32 v0, v25, v65
	v_mul_f32_e32 v1, v9, v65
	v_cvt_pk_bf16_f32 v0, v0, v1
	ds_write_b16 v72, v0 offset:2176
	ds_write_b16_d16_hi v72, v0 offset:2240
	v_mul_f32_e32 v0, v26, v66
	v_mul_f32_e32 v1, v10, v66
	v_cvt_pk_bf16_f32 v0, v0, v1
	ds_write_b16 v72, v0 offset:2304
	ds_write_b16_d16_hi v72, v0 offset:2368
	v_mul_f32_e32 v0, v27, v67
	v_mul_f32_e32 v1, v11, v67
	v_cvt_pk_bf16_f32 v0, v0, v1
	ds_write_b16 v72, v0 offset:2432
	ds_write_b16_d16_hi v72, v0 offset:2496
	v_mul_f32_e32 v0, v28, v68
	v_mul_f32_e32 v1, v12, v68
	v_cvt_pk_bf16_f32 v0, v0, v1
	ds_write_b16 v72, v0 offset:3072
	ds_write_b16_d16_hi v72, v0 offset:3136
	v_mul_f32_e32 v0, v29, v69
	v_mul_f32_e32 v1, v13, v69
	v_cvt_pk_bf16_f32 v0, v0, v1
	ds_write_b16 v72, v0 offset:3200
	ds_write_b16_d16_hi v72, v0 offset:3264
	v_mul_f32_e32 v0, v30, v70
	v_mul_f32_e32 v1, v14, v70
	v_cvt_pk_bf16_f32 v0, v0, v1
	ds_write_b16 v72, v0 offset:3328
	ds_write_b16_d16_hi v72, v0 offset:3392
	v_mul_f32_e32 v0, v31, v71
	v_mul_f32_e32 v1, v15, v71
	v_cvt_pk_bf16_f32 v0, v0, v1
	ds_write_b16 v72, v0 offset:3456
	ds_write_b16_d16_hi v72, v0 offset:3520
	s_waitcnt lgkmcnt(0)
	ds_read_b128 v[0:3], v83
	v_lshl_add_u64 v[4:5], v[36:37], 0, s[34:35]
	s_waitcnt lgkmcnt(0)
	global_store_dwordx4 v[4:5], v[0:3], off offset:0 sc1 nt
	s_nop 1
	ds_read_b128 v[0:3], v44
	v_lshl_add_u64 v[4:5], v[38:39], 0, s[34:35]
	s_waitcnt lgkmcnt(0)
	global_store_dwordx4 v[4:5], v[0:3], off offset:0 sc1 nt
	s_nop 1
	ds_read_b128 v[0:3], v45
	v_lshl_add_u64 v[4:5], v[40:41], 0, s[34:35]
	s_waitcnt lgkmcnt(0)
	global_store_dwordx4 v[4:5], v[0:3], off offset:0 sc1 nt
	s_nop 1
	ds_read_b128 v[0:3], v46
	v_lshl_add_u64 v[4:5], v[42:43], 0, s[34:35]
	s_waitcnt lgkmcnt(0)
	global_store_dwordx4 v[4:5], v[0:3], off offset:0 sc1 nt
	s_nop 1
	v_readlane_b32 s1, v254, 50
	s_waitcnt lgkmcnt(0)
	s_add_i32 s26, s26, s1
	s_add_i32 s10, s10, 1
	s_cmpk_gt_i32 s26, 0x4ff
	s_cbranch_scc1 .LBB0_520
